# S5: delay the backward-direction waves (4-7) by about half a chunk at task start and after the mid-task barrier so LDS-heavy and VALU-heavy parts of SIMD partners overlap
# speedup vs baseline: 1.0093x; 1.0074x over previous
; __device__ __forceinline__ unsigned cvt_pk_bf16(float lo, float hi) { f32x2_t v = {lo, hi}; bf16x2_t b = __builtin_convertvector(v, bf16x2_t); return __builtin_bit_cast(unsigned, b); }
; __device__ __forceinline__ void s5_phase(LAS unsigned char* lds, CParams* pp, int layer, int G, int c) {
;     ...
;         for (int kb = 0; kb < 4; ++kb) { const int pc = kb * 16 + lq * 4; const f32x4 cr = *(const f32x4*)(pp->in[9] + (pg * 16 + l15) * 64 + pc), ci = *(const f32x4*)(pp->in[10] + (pg * 16 + l15) * 64 + pc);
;             const unsigned w0 = cvt_pk_bf16(cr[0], -ci[0]), w1 = cvt_pk_bf16(cr[1], -ci[1]), w2 = cvt_pk_bf16(cr[2], -ci[2]), w3 = cvt_pk_bf16(cr[3], -ci[3]);
;             bf16x8 f; f[0] = (short)(w0 & 0xffff); f[1] = (short)(w0 >> 16); f[2] = (short)(w1 & 0xffff); f[3] = (short)(w1 >> 16); f[4] = (short)(w2 & 0xffff); f[5] = (short)(w2 >> 16); f[6] = (short)(w3 & 0xffff); f[7] = (short)(w3 >> 16);
;             Cf[kb] = f; }
;         const f32x4 dsk = *(const f32x4*)(pp->in[11] + layer * DM + g * 16 + 4 * lq);
;         float xr = 0.f, xi = 0.f;
;         const size_t colA = (size_t)g * 16 + (lq & 1) * 8, colO = (size_t)g * 16 + 4 * lq;
;     ...
;         bf16x8 Af_n[2]; u32x2 uo_n[2]; u32x2 yp_n[2];
; #pragma unroll
;         for (int tb = 0; tb < 2; ++tb) { const size_t t0 = S5_TOK(0, tb); Af_n[tb] = *(const bf16x8*)(U + t0 * DM + colA); uo_n[tb] = *(const u32x2*)(U + t0 * DM + colO); yp_n[tb] = (u32x2){0u, 0u}; }
;         for (int k = 0; k < 64; ++k) {
;             if (k == 32) { __syncthreads();
; #pragma unroll
;                 for (int tb = 0; tb < 2; ++tb) yp_n[tb] = *(const u32x2*)(YP + S5_TOK(32, tb) * DM + colO); }
.LBB0_361:
	s_or_b64 exec, exec, s[88:89]
	s_lshl_b64 s[60:61], s[64:65], 12
	v_lshl_or_b32 v28, v78, 2, s60
	v_mov_b32_e32 v29, s61
	v_lshl_add_u64 v[54:55], v[104:105], 0, v[28:29]
	v_lshl_add_u64 v[52:53], v[102:103], 0, v[28:29]
	global_load_dwordx4 v[28:31], v[54:55], off
	v_mul_f32_e32 v108, v27, v25
	s_waitcnt lgkmcnt(0)
	global_load_dwordx4 v[24:27], v[52:53], off
	s_ashr_i32 s60, s2, 5
	s_lshl_b32 s5, s4, 4
	s_ashr_i32 s61, s60, 31
	s_lshl_b32 s36, s4, 6
	v_or_b32_e32 v120, s5, v76
	v_mov_b32_e32 v122, 0
	v_mov_b32_e32 v109, v108
	v_xor_b32_e32 v106, 0x80000000, v107
	s_mov_b32 s67, 63
	v_mov_b32_e32 v118, 0
	v_mov_b32_e32 v119, 0
	v_mov_b32_e32 v116, 0
	v_mov_b32_e32 v117, 0
	v_mov_b32_e32 v123, v122
	s_waitcnt vmcnt(1)
	v_xor_b32_e32 v28, 0x80000000, v28
	s_waitcnt vmcnt(0)
	v_cvt_pk_bf16_f32 v28, v24, v28
	v_xor_b32_e32 v24, 0x80000000, v29
	v_cvt_pk_bf16_f32 v29, v25, v24
	v_xor_b32_e32 v24, 0x80000000, v30
	v_cvt_pk_bf16_f32 v30, v26, v24
	v_xor_b32_e32 v24, 0x80000000, v31
	v_cvt_pk_bf16_f32 v31, v27, v24
	global_load_dwordx4 v[24:27], v[52:53], off offset:64
	global_load_dwordx4 v[40:43], v[54:55], off offset:64
	s_waitcnt vmcnt(0)
	v_xor_b32_e32 v40, 0x80000000, v40
	v_cvt_pk_bf16_f32 v44, v24, v40
	v_xor_b32_e32 v24, 0x80000000, v41
	v_cvt_pk_bf16_f32 v45, v25, v24
	v_xor_b32_e32 v24, 0x80000000, v42
	v_cvt_pk_bf16_f32 v46, v26, v24
	v_xor_b32_e32 v24, 0x80000000, v43
	v_cvt_pk_bf16_f32 v47, v27, v24
	global_load_dwordx4 v[24:27], v[52:53], off offset:128
	global_load_dwordx4 v[40:43], v[54:55], off offset:128
	s_waitcnt vmcnt(0)
	v_xor_b32_e32 v40, 0x80000000, v40
	v_cvt_pk_bf16_f32 v48, v24, v40
	v_xor_b32_e32 v24, 0x80000000, v41
	v_cvt_pk_bf16_f32 v49, v25, v24
	v_xor_b32_e32 v24, 0x80000000, v42
	v_cvt_pk_bf16_f32 v50, v26, v24
	v_xor_b32_e32 v24, 0x80000000, v43
	v_cvt_pk_bf16_f32 v51, v27, v24
	global_load_dwordx4 v[24:27], v[52:53], off offset:192
	global_load_dwordx4 v[40:43], v[54:55], off offset:192
	v_or_b32_e32 v54, s5, v82
	s_lshl_b64 s[4:5], s[60:61], 11
	v_mov_b32_e32 v53, s5
	v_or_b32_e32 v52, s4, v84
	v_lshlrev_b64 v[52:53], 12, v[52:53]
	v_lshl_add_u64 v[52:53], s[80:81], 0, v[52:53]
	v_lshlrev_b32_e32 v178, 1, v54
	v_lshl_add_u64 v[54:55], v[52:53], 0, v[178:179]
	global_load_dwordx4 v[64:67], v[54:55], off
	v_lshlrev_b32_e32 v54, 1, v120
	v_mov_b32_e32 v55, v179
	s_mov_b64 s[60:61], 0x10000
	v_lshl_add_u64 v[56:57], v[52:53], 0, v[54:55]
	v_lshl_add_u64 v[52:53], v[52:53], 0, s[60:61]
	global_load_dwordx2 v[114:115], v[56:57], off
	v_lshl_add_u64 v[56:57], v[52:53], 0, v[178:179]
	v_lshl_add_u64 v[52:53], v[52:53], 0, v[54:55]
	global_load_dwordx4 v[60:63], v[56:57], off
	global_load_dwordx2 v[110:111], v[52:53], off
	v_mov_b32_e32 v53, s5
	v_or_b32_e32 v52, s4, v86
	v_lshl_add_u64 v[124:125], s[14:15], 0, v[54:55]
	v_lshlrev_b64 v[52:53], 12, v[52:53]
	v_lshl_add_u64 v[130:131], v[124:125], 0, v[52:53]
	v_mov_b32_e32 v113, s5
	v_or_b32_e32 v112, s4, v68
	v_lshl_add_u64 v[126:127], s[80:81], 0, v[178:179]
	v_lshl_add_u64 v[128:129], s[80:81], 0, v[54:55]
	v_lshl_add_u64 v[132:133], v[130:131], 0, s[60:61]
	v_lshl_add_u64 v[134:135], s[58:59], 0, v[54:55]
	s_waitcnt vmcnt(4)
	v_xor_b32_e32 v40, 0x80000000, v40
	v_cvt_pk_bf16_f32 v40, v24, v40
	v_xor_b32_e32 v24, 0x80000000, v41
	v_cvt_pk_bf16_f32 v41, v25, v24
	v_xor_b32_e32 v24, 0x80000000, v42
	v_cvt_pk_bf16_f32 v42, v26, v24
	v_xor_b32_e32 v24, 0x80000000, v43
	v_cvt_pk_bf16_f32 v43, v27, v24
	v_lshl_add_u64 v[24:25], v[80:81], 0, s[36:37]
	global_load_dwordx4 v[24:27], v[24:25], off
	v_add_u32_e32 v93, s10, v69
	v_add_u32_e32 v95, s11, v69
	v_add_u32_e32 v97, s22, v69
	v_add_u32_e32 v99, s23, v69
	v_add_u32_e32 v101, s35, v69
	v_add_u32_e32 v121, s54, v69
	v_add_u32_e32 v146, s91, v69
	v_add_u32_e32 v147, s92, v69
	v_add_u32_e32 v148, s93, v69
	v_add_u32_e32 v149, s94, v69
	v_add_u32_e32 v150, s95, v69
	v_add_u32_e32 v151, s96, v69
	v_add_u32_e32 v152, s97, v69
	v_add_u32_e32 v144, s55, v69
	v_add_u32_e32 v145, s90, v69
	v_add_u32_e32 v153, s6, v69
	v_add_u32_e32 v154, s38, v69
	v_add_u32_e32 v155, s39, v69
	v_add_u32_e32 v156, s19, v69
	v_add_u32_e32 v157, s72, v69
	v_add_u32_e32 v158, s73, v69
	v_add_u32_e32 v159, s16, v69
	v_add_u32_e32 v160, s17, v69
	v_add_u32_e32 v161, s30, v69
	v_add_u32_e32 v163, s31, v69
	v_add_u32_e32 v164, s26, v69
	v_add_u32_e32 v165, s27, v69
	v_add_u32_e32 v166, s70, v69
	v_add_u32_e32 v167, s71, v69
	v_add_u32_e32 v168, s52, v69
	v_add_u32_e32 v169, s53, v69
	v_add_u32_e32 v170, s50, v69
	v_add_u32_e32 v162, 0x1000, v89
	s_cmp_eq_u64 s[78:79], 0
	s_cbranch_scc0 .Ls5_nostag_a
	s_sleep 40
.Ls5_nostag_a:
	s_cmp_lg_u32 s67, 31
	s_cbranch_scc1 .LBB0_363
.LBB0_362:
	s_barrier
	s_cmp_eq_u64 s[78:79], 0
	s_cbranch_scc0 .Ls5_nostag_b
	s_sleep 40
.Ls5_nostag_b:
	global_load_dwordx2 v[118:119], v[130:131], off
	global_load_dwordx2 v[116:117], v[132:133], off
